# v13 + dilated-attention (mixer B) row-max trees at the mask join rewritten as 16 v_max3 ops (no canonicalize copies), the two interleaved score adds kept in front
# speedup vs baseline: 1.0069x; 1.0069x over previous
.LBB0_635:
	s_nop 4
	v_add_f32_e32 v159, v111, v1
	v_add_f32_e32 v1, v95, v237
	v_max3_f32 v4, v3, v161, v6
	v_max3_f32 v80, v164, v7, v165
	v_max3_f32 v4, v4, v160, v2
	v_max3_f32 v80, v80, v10, v168
	v_max3_f32 v4, v4, v11, v169
	v_max3_f32 v80, v80, v156, v172
	v_max3_f32 v4, v4, v157, v173
	v_max3_f32 v80, v80, v14, v170
	v_max3_f32 v4, v4, v15, v171
	v_max3_f32 v80, v80, v12, v166
	v_max3_f32 v4, v4, v13, v167
	v_max3_f32 v80, v80, v8, v162
	v_max3_f32 v4, v4, v9, v163
	v_max3_f32 v80, v80, v0, v158
	v_max3_f32 v4, v4, v159, v1
	v_max_f32_e32 v4, v4, v80
	ds_bpermute_b32 v80, v174, v4
	s_andn2_b64 vcc, exec, s[18:19]
	s_waitcnt lgkmcnt(0)
	v_max_f32_e32 v80, v80, v80
	v_max_f32_e32 v4, v4, v80
	v_cmp_lt_f32_e64 s[66:67], s38, v4
	s_cbranch_vccnz .LBB0_637
	s_cmp_lg_u64 s[66:67], 0
	s_cselect_b64 s[20:21], -1, 0

.LBB0_1178:
	s_nop 4
	v_add_f32_e32 v159, v111, v1
	v_add_f32_e32 v1, v95, v227
	v_max3_f32 v4, v3, v161, v6
	v_max3_f32 v80, v164, v7, v165
	v_max3_f32 v4, v4, v160, v2
	v_max3_f32 v80, v80, v10, v168
	v_max3_f32 v4, v4, v11, v169
	v_max3_f32 v80, v80, v156, v172
	v_max3_f32 v4, v4, v157, v173
	v_max3_f32 v80, v80, v14, v170
	v_max3_f32 v4, v4, v15, v171
	v_max3_f32 v80, v80, v12, v166
	v_max3_f32 v4, v4, v13, v167
	v_max3_f32 v80, v80, v8, v162
	v_max3_f32 v4, v4, v9, v163
	v_max3_f32 v80, v80, v0, v158
	v_max3_f32 v4, v4, v159, v1
	v_max_f32_e32 v4, v4, v80
	ds_bpermute_b32 v80, v174, v4
	s_andn2_b64 vcc, exec, s[18:19]
	s_waitcnt lgkmcnt(0)
	v_max_f32_e32 v80, v80, v80
	v_max_f32_e32 v4, v4, v80
	v_cmp_lt_f32_e64 s[66:67], s38, v4
	s_cbranch_vccnz .LBB0_1180
	s_cmp_lg_u64 s[66:67], 0
	s_cselect_b64 s[20:21], -1, 0
